# prologue rmsnorm fifth row per wave (sample / memory rows): hand-written path, row and gain vector loaded together
# speedup vs baseline: 1.0140x; 1.0140x over previous
.LBB0_24:
	s_cmpk_lg_i32 s26, 0x100
	s_cbranch_scc1 .Lp0r5_orig
	s_waitcnt lgkmcnt(0)
	v_and_b32_e32 v154, 63, v164
	v_lshlrev_b32_e32 v155, 4, v154
	v_add_u32_e32 v156, 0x1000, v155
	v_lshlrev_b32_e32 v157, 3, v154
	v_lshlrev_b32_e32 v158, 2, v154
	s_cmpk_lt_u32 s24, 0x400
	s_cselect_b32 s98, s10, s14
	s_cselect_b32 s99, s11, s15
	s_cselect_b32 s100, s34, s38
	s_cselect_b32 s101, s35, s39
	s_and_b32 s93, s24, 0x3ff
	s_lshl_b32 s93, s93, 13
	s_add_u32 s98, s98, s93
	s_addc_u32 s99, s99, 0
	global_load_dwordx4 v[166:169], v155, s[98:99]
	global_load_dwordx4 v[170:173], v155, s[98:99] offset:1024
	global_load_dwordx4 v[174:177], v155, s[98:99] offset:2048
	global_load_dwordx4 v[178:181], v155, s[98:99] offset:3072
	global_load_dwordx4 v[182:185], v156, s[98:99]
	global_load_dwordx4 v[186:189], v156, s[98:99] offset:1024
	global_load_dwordx4 v[190:193], v156, s[98:99] offset:2048
	global_load_dwordx4 v[194:197], v156, s[98:99] offset:3072
	global_load_dwordx4 v[198:201], v155, s[100:101]
	global_load_dwordx4 v[202:205], v155, s[100:101] offset:1024
	global_load_dwordx4 v[206:209], v155, s[100:101] offset:2048
	global_load_dwordx4 v[210:213], v155, s[100:101] offset:3072
	global_load_dwordx4 v[214:217], v156, s[100:101]
	global_load_dwordx4 v[218:221], v156, s[100:101] offset:1024
	global_load_dwordx4 v[222:225], v156, s[100:101] offset:2048
	global_load_dwordx4 v[228:231], v156, s[100:101] offset:3072
	s_add_i32 s93, s24, 0x2000
	s_lshl_b32 s93, s93, 12
	s_add_u32 s70, s36, s93
	s_addc_u32 s71, s37, 0
	s_waitcnt vmcnt(8)
	v_mul_f32_e32 v159, v166, v166
	v_fmac_f32_e32 v159, v167, v167
	v_fmac_f32_e32 v159, v168, v168
	v_fmac_f32_e32 v159, v169, v169
	v_fmac_f32_e32 v159, v170, v170
	v_fmac_f32_e32 v159, v171, v171
	v_fmac_f32_e32 v159, v172, v172
	v_fmac_f32_e32 v159, v173, v173
	v_fmac_f32_e32 v159, v174, v174
	v_fmac_f32_e32 v159, v175, v175
	v_fmac_f32_e32 v159, v176, v176
	v_fmac_f32_e32 v159, v177, v177
	v_fmac_f32_e32 v159, v178, v178
	v_fmac_f32_e32 v159, v179, v179
	v_fmac_f32_e32 v159, v180, v180
	v_fmac_f32_e32 v159, v181, v181
	v_fmac_f32_e32 v159, v182, v182
	v_fmac_f32_e32 v159, v183, v183
	v_fmac_f32_e32 v159, v184, v184
	v_fmac_f32_e32 v159, v185, v185
	v_fmac_f32_e32 v159, v186, v186
	v_fmac_f32_e32 v159, v187, v187
	v_fmac_f32_e32 v159, v188, v188
	v_fmac_f32_e32 v159, v189, v189
	v_fmac_f32_e32 v159, v190, v190
	v_fmac_f32_e32 v159, v191, v191
	v_fmac_f32_e32 v159, v192, v192
	v_fmac_f32_e32 v159, v193, v193
	v_fmac_f32_e32 v159, v194, v194
	v_fmac_f32_e32 v159, v195, v195
	v_fmac_f32_e32 v159, v196, v196
	v_fmac_f32_e32 v159, v197, v197
	v_xor_b32_e32 v160, 4, v158
	ds_bpermute_b32 v161, v160, v159
	s_waitcnt lgkmcnt(0)
	v_add_f32_e32 v159, v159, v161
	v_xor_b32_e32 v160, 8, v158
	ds_bpermute_b32 v161, v160, v159
	s_waitcnt lgkmcnt(0)
	v_add_f32_e32 v159, v159, v161
	v_xor_b32_e32 v160, 16, v158
	ds_bpermute_b32 v161, v160, v159
	s_waitcnt lgkmcnt(0)
	v_add_f32_e32 v159, v159, v161
	v_xor_b32_e32 v160, 32, v158
	ds_bpermute_b32 v161, v160, v159
	s_waitcnt lgkmcnt(0)
	v_add_f32_e32 v159, v159, v161
	v_xor_b32_e32 v160, 64, v158
	ds_bpermute_b32 v161, v160, v159
	s_waitcnt lgkmcnt(0)
	v_add_f32_e32 v159, v159, v161
	v_xor_b32_e32 v160, 128, v158
	ds_bpermute_b32 v161, v160, v159
	s_waitcnt lgkmcnt(0)
	v_add_f32_e32 v159, v159, v161
	v_mov_b32_e32 v162, 0x3a000000
	v_mov_b32_e32 v163, 0x358637bd
	v_fma_f32 v159, v159, v162, v163
	v_rsq_f32_e32 v159, v159
	s_waitcnt vmcnt(0)
	v_mul_f32_e32 v166, v166, v159
	v_mul_f32_e32 v166, v166, v198
	v_mul_f32_e32 v167, v167, v159
	v_mul_f32_e32 v167, v167, v199
	v_mul_f32_e32 v168, v168, v159
	v_mul_f32_e32 v168, v168, v200
	v_mul_f32_e32 v169, v169, v159
	v_mul_f32_e32 v169, v169, v201
	v_cvt_pk_bf16_f32 v166, v166, v167
	v_cvt_pk_bf16_f32 v167, v168, v169
	global_store_dwordx2 v157, v[166:167], s[70:71]
	v_mul_f32_e32 v170, v170, v159
	v_mul_f32_e32 v170, v170, v202
	v_mul_f32_e32 v171, v171, v159
	v_mul_f32_e32 v171, v171, v203
	v_mul_f32_e32 v172, v172, v159
	v_mul_f32_e32 v172, v172, v204
	v_mul_f32_e32 v173, v173, v159
	v_mul_f32_e32 v173, v173, v205
	v_cvt_pk_bf16_f32 v170, v170, v171
	v_cvt_pk_bf16_f32 v171, v172, v173
	global_store_dwordx2 v157, v[170:171], s[70:71] offset:512
	v_mul_f32_e32 v174, v174, v159
	v_mul_f32_e32 v174, v174, v206
	v_mul_f32_e32 v175, v175, v159
	v_mul_f32_e32 v175, v175, v207
	v_mul_f32_e32 v176, v176, v159
	v_mul_f32_e32 v176, v176, v208
	v_mul_f32_e32 v177, v177, v159
	v_mul_f32_e32 v177, v177, v209
	v_cvt_pk_bf16_f32 v174, v174, v175
	v_cvt_pk_bf16_f32 v175, v176, v177
	global_store_dwordx2 v157, v[174:175], s[70:71] offset:1024
	v_mul_f32_e32 v178, v178, v159
	v_mul_f32_e32 v178, v178, v210
	v_mul_f32_e32 v179, v179, v159
	v_mul_f32_e32 v179, v179, v211
	v_mul_f32_e32 v180, v180, v159
	v_mul_f32_e32 v180, v180, v212
	v_mul_f32_e32 v181, v181, v159
	v_mul_f32_e32 v181, v181, v213
	v_cvt_pk_bf16_f32 v178, v178, v179
	v_cvt_pk_bf16_f32 v179, v180, v181
	global_store_dwordx2 v157, v[178:179], s[70:71] offset:1536
	v_mul_f32_e32 v182, v182, v159
	v_mul_f32_e32 v182, v182, v214
	v_mul_f32_e32 v183, v183, v159
	v_mul_f32_e32 v183, v183, v215
	v_mul_f32_e32 v184, v184, v159
	v_mul_f32_e32 v184, v184, v216
	v_mul_f32_e32 v185, v185, v159
	v_mul_f32_e32 v185, v185, v217
	v_cvt_pk_bf16_f32 v182, v182, v183
	v_cvt_pk_bf16_f32 v183, v184, v185
	global_store_dwordx2 v157, v[182:183], s[70:71] offset:2048
	v_mul_f32_e32 v186, v186, v159
	v_mul_f32_e32 v186, v186, v218
	v_mul_f32_e32 v187, v187, v159
	v_mul_f32_e32 v187, v187, v219
	v_mul_f32_e32 v188, v188, v159
	v_mul_f32_e32 v188, v188, v220
	v_mul_f32_e32 v189, v189, v159
	v_mul_f32_e32 v189, v189, v221
	v_cvt_pk_bf16_f32 v186, v186, v187
	v_cvt_pk_bf16_f32 v187, v188, v189
	global_store_dwordx2 v157, v[186:187], s[70:71] offset:2560
	v_mul_f32_e32 v190, v190, v159
	v_mul_f32_e32 v190, v190, v222
	v_mul_f32_e32 v191, v191, v159
	v_mul_f32_e32 v191, v191, v223
	v_mul_f32_e32 v192, v192, v159
	v_mul_f32_e32 v192, v192, v224
	v_mul_f32_e32 v193, v193, v159
	v_mul_f32_e32 v193, v193, v225
	v_cvt_pk_bf16_f32 v190, v190, v191
	v_cvt_pk_bf16_f32 v191, v192, v193
	global_store_dwordx2 v157, v[190:191], s[70:71] offset:3072
	v_mul_f32_e32 v194, v194, v159
	v_mul_f32_e32 v194, v194, v228
	v_mul_f32_e32 v195, v195, v159
	v_mul_f32_e32 v195, v195, v229
	v_mul_f32_e32 v196, v196, v159
	v_mul_f32_e32 v196, v196, v230
	v_mul_f32_e32 v197, v197, v159
	v_mul_f32_e32 v197, v197, v231
	v_cvt_pk_bf16_f32 v194, v194, v195
	v_cvt_pk_bf16_f32 v195, v196, v197
	global_store_dwordx2 v157, v[194:195], s[70:71] offset:3584
	s_branch .LBB0_44
